# w_in GEMM: the 84 second-round units are split along K between two workgroups (f32 partial through free workspace, flag word), rest as previous
# baseline (speedup 1.0000x reference)
.LBB0_147:
	v_bfe_u32 v16, v0, 4, 2
	s_add_u32 s12, s12, 0xb200000
	v_and_b32_e32 v166, 15, v0
	v_lshlrev_b32_e32 v18, 4, v16
	v_lshlrev_b32_e32 v19, 2, v0
	s_addc_u32 s13, s13, 0
	s_and_b32 s18, s15, 3
	v_lshl_or_b32 v18, v166, 6, v18
	s_lshl_b32 s15, s16, 13
	v_and_b32_e32 v19, 32, v19
	s_add_i32 m0, s23, 0x18000
	v_lshl_add_u64 v[8:9], v[8:9], 0, s[98:99]
	s_lshl_b32 s51, s16, 6
	v_bitop3_b32 v20, v18, s15, v19 bitop3:0xde
	s_lshl_b32 s19, s18, 5
	s_lshl_b32 s15, s18, 12
	s_waitcnt vmcnt(2)
	s_barrier
	global_load_lds_dwordx4 v[8:9], off
	v_lshl_add_u64 v[6:7], v[6:7], 0, s[98:99]
	s_add_i32 m0, s23, 0x1a000
	s_add_i32 s52, s23, 0x8000
	s_add_i32 s53, s23, 0xa000
	global_load_lds_dwordx4 v[6:7], off
	v_lshl_add_u64 v[2:3], v[2:3], 0, s[98:99]
	s_mov_b32 m0, s52
	s_add_u32 s16, s26, 0x40080
	global_load_lds_dwordx4 v[2:3], off
	v_lshl_add_u64 v[2:3], v[4:5], 0, s[98:99]
	s_mov_b32 m0, s53
	s_addc_u32 s17, s27, 0
	global_load_lds_dwordx4 v[2:3], off
	s_add_i32 m0, s23, 0x1c000
	v_lshl_add_u64 v[2:3], s[16:17], 0, v[132:133]
	global_load_lds_dwordx4 v[2:3], off
	v_lshl_add_u64 v[2:3], s[16:17], 0, v[136:137]
	s_add_i32 m0, s23, 0x1e000
	v_and_b32_e32 v0, 16, v0
	global_load_lds_dwordx4 v[2:3], off
	v_cmp_eq_u32_e32 vcc, 0, v0
	v_lshlrev_b32_e32 v0, 14, v10
	v_and_b32_e32 v0, 0xffff8000, v0
	v_lshl_add_u32 v0, v11, 11, v0
	v_and_b32_e32 v2, 1, v10
	v_lshl_or_b32 v0, v2, 6, v0
	s_cmpk_lt_u32 s14, 0x100
	v_lshl_add_u32 v138, v12, 1, v0
	v_lshlrev_b32_e32 v0, 14, v13
	v_bitop3_b32 v167, v18, s15, v19 bitop3:0xde
	s_cselect_b64 s[14:15], -1, 0
	s_cmp_gt_u32 s18, 1
	v_and_b32_e32 v0, 0xffff8000, v0
	v_lshlrev_b32_e32 v17, 3, v16
	s_waitcnt vmcnt(6)
	s_cselect_b64 s[16:17], -1, 0
	s_add_i32 s20, s19, 0x440
	v_lshl_add_u32 v0, v14, 11, v0
	v_and_b32_e32 v2, 1, v13
	v_or_b32_e32 v169, s20, v17
	v_lshl_or_b32 v0, v2, 6, v0
	v_cmp_gt_u32_e64 s[38:39], 2, v16
	s_mov_b32 s54, 0
	v_cndmask_b32_e64 v168, v231, 1.0, vcc
	v_add_u32_e32 v170, 64, v169
	v_lshl_or_b32 v171, s18, 6, v17
	v_or_b32_e32 v172, s19, v17
	v_mov_b32_e32 v139, v1
	v_lshl_add_u32 v140, v15, 1, v0
	v_mov_b32_e32 v141, v1
	v_add_u32_e32 v173, 0, v20
	s_barrier
	s_mov_b32 s64, 0
	s_branch .LBB0_150

.LBB0_149:
	s_andn2_b64 vcc, exec, s[18:19]
	s_mov_b32 s64, s65
	s_mov_b32 s42, s20
	s_mov_b32 s22, s28
	s_mov_b64 s[26:27], s[30:31]
	s_mov_b64 s[40:41], s[24:25]
	s_cbranch_vccz .LBB0_186
.LBB0_150:
	s_add_i32 s54, s54, 1
	s_mul_i32 s24, s54, s46
	s_add_i32 s24, s24, s2
	s_mov_b32 s65, 0
	s_cmp_lg_u32 s54, 1
	s_cbranch_scc1 .Lks_n
	s_cmpk_lg_u32 s46, 0x100
	s_cbranch_scc1 .Lks_n
	s_movk_i32 s24, 0x154
	s_cmpk_gt_u32 s2, 0xa7
	s_cbranch_scc1 .Lks_n
	s_lshr_b32 s24, s2, 1
	s_addk_i32 s24, 0x100
	s_and_b32 s65, s2, 1
	s_add_i32 s65, s65, 1
.Lks_n:
	s_cmpk_lt_i32 s24, 0x154
	s_cselect_b64 s[18:19], -1, 0
	s_cmpk_gt_i32 s24, 0x153
	s_cbranch_scc1 .LBB0_159
	s_and_b32 s25, s24, 7
	s_cmp_gt_u32 s25, 3
	s_mov_b64 s[20:21], -1
	s_cbranch_scc0 .LBB0_153
	s_mul_i32 s20, s25, 42
	s_add_i32 s28, s20, 4
	s_mov_b64 s[20:21], 0

.LBB0_159:
	s_ashr_i32 s29, s28, 31
	s_lshl_b64 s[24:25], s[28:29], 19
	s_add_u32 s24, s34, s24
	s_addc_u32 s25, s35, s25
	s_cmp_eq_u32 s65, 2
	s_cselect_b32 s66, 0x300, 0
	s_add_u32 s24, s24, s66
	s_addc_u32 s25, s25, 0
	s_and_b64 s[30:31], s[18:19], exec
	s_cselect_b32 s29, s25, s41
	s_cselect_b32 s43, s24, s40
	s_ashr_i32 s21, s20, 31
	s_lshl_b64 s[30:31], s[20:21], 19
	s_add_u32 s30, s36, s30
	s_addc_u32 s31, s37, s31
	s_add_u32 s30, s30, s66
	s_addc_u32 s31, s31, 0
	s_and_b64 s[56:57], s[18:19], exec
	s_cselect_b32 s21, s31, s27
	s_cselect_b32 s55, s30, s26
	s_add_u32 s40, s40, 0x40080
	s_addc_u32 s41, s41, 0
	s_add_u32 s56, s26, 0x100
	s_addc_u32 s57, s27, 0
	s_mov_b32 s58, -2
	s_cmp_eq_u32 s64, 1
	s_cselect_b32 s58, 8, s58
	s_cmp_eq_u32 s64, 2
	s_cselect_b32 s58, 4, s58
	s_add_u32 s26, s40, 0xfffc0080
	s_addc_u32 s27, s41, -1
	s_add_i32 s59, 0, 0x10000
	s_cmp_eq_u32 s58, 12
	s_cselect_b32 vcc_hi, s29, s27
	s_cselect_b32 vcc_lo, s43, s26
	v_add_u32_e32 v0, s59, v167
	s_cselect_b32 s27, s21, s57
	s_cselect_b32 s26, s55, s56
	s_add_i32 s62, 0, 0x14000
	ds_read_b128 v[142:145], v0
	ds_read_b128 v[146:149], v0 offset:1024
	ds_read_b128 v[150:153], v0 offset:2048
	ds_read_b128 v[154:157], v0 offset:3072
	v_add_u32_e32 v0, s62, v167
	ds_read_b128 v[158:161], v0
	ds_read_b128 v[162:165], v0 offset:1024
	ds_read_b128 v[174:177], v0 offset:2048
	ds_read_b128 v[178:181], v0 offset:3072
	v_lshl_add_u64 v[214:215], s[40:41], 0, v[138:139]
	s_add_i32 m0, s23, 0xc000
	ds_read_b128 v[182:185], v173
	ds_read_b128 v[186:189], v173 offset:1024
	ds_read_b128 v[190:193], v173 offset:2048
	ds_read_b128 v[194:197], v173 offset:3072
	ds_read_b128 v[198:201], v173 offset:4096
	ds_read_b128 v[202:205], v173 offset:5120
	ds_read_b128 v[206:209], v173 offset:6144
	ds_read_b128 v[210:213], v173 offset:7168
	global_load_lds_dwordx4 v[214:215], off
	v_lshl_add_u64 v[214:215], s[40:41], 0, v[140:141]
	s_add_i32 m0, s23, 0xe000
	s_nop 0
	global_load_lds_dwordx4 v[214:215], off
	s_waitcnt vmcnt(8)
	s_waitcnt lgkmcnt(0)
	s_barrier
	s_waitcnt lgkmcnt(0)
	v_mfma_f32_16x16x32_bf16 v[126:129], v[142:145], v[182:185], 0
	v_mfma_f32_16x16x32_bf16 v[122:125], v[150:153], v[182:185], 0
	v_mfma_f32_16x16x32_bf16 v[118:121], v[142:145], v[190:193], 0
	v_mfma_f32_16x16x32_bf16 v[114:117], v[150:153], v[190:193], 0
	v_mfma_f32_16x16x32_bf16 v[110:113], v[142:145], v[198:201], 0
	v_mfma_f32_16x16x32_bf16 v[106:109], v[150:153], v[198:201], 0
	v_mfma_f32_16x16x32_bf16 v[102:105], v[142:145], v[206:209], 0
	v_mfma_f32_16x16x32_bf16 v[98:101], v[150:153], v[206:209], 0
	v_mfma_f32_16x16x32_bf16 v[126:129], v[146:149], v[186:189], v[126:129]
	v_mfma_f32_16x16x32_bf16 v[122:125], v[154:157], v[186:189], v[122:125]
	v_mfma_f32_16x16x32_bf16 v[118:121], v[146:149], v[194:197], v[118:121]
	v_mfma_f32_16x16x32_bf16 v[114:117], v[154:157], v[194:197], v[114:117]
	v_mfma_f32_16x16x32_bf16 v[110:113], v[146:149], v[202:205], v[110:113]
	v_mfma_f32_16x16x32_bf16 v[106:109], v[154:157], v[202:205], v[106:109]
	v_mfma_f32_16x16x32_bf16 v[102:105], v[146:149], v[210:213], v[102:105]
	v_mfma_f32_16x16x32_bf16 v[98:101], v[154:157], v[210:213], v[98:101]
	v_mfma_f32_16x16x32_bf16 v[82:85], v[158:161], v[182:185], 0
	v_mfma_f32_16x16x32_bf16 v[74:77], v[174:177], v[182:185], 0
	v_mfma_f32_16x16x32_bf16 v[70:73], v[158:161], v[190:193], 0
	v_mfma_f32_16x16x32_bf16 v[62:65], v[174:177], v[190:193], 0
	v_mfma_f32_16x16x32_bf16 v[54:57], v[158:161], v[198:201], 0
	v_mfma_f32_16x16x32_bf16 v[46:49], v[174:177], v[198:201], 0
	v_mfma_f32_16x16x32_bf16 v[38:41], v[158:161], v[206:209], 0
	v_mfma_f32_16x16x32_bf16 v[34:37], v[174:177], v[206:209], 0
	v_mfma_f32_16x16x32_bf16 v[82:85], v[162:165], v[186:189], v[82:85]
	v_mfma_f32_16x16x32_bf16 v[74:77], v[178:181], v[186:189], v[74:77]
	v_mfma_f32_16x16x32_bf16 v[70:73], v[162:165], v[194:197], v[70:73]
	v_mfma_f32_16x16x32_bf16 v[62:65], v[178:181], v[194:197], v[62:65]
	v_mfma_f32_16x16x32_bf16 v[54:57], v[162:165], v[202:205], v[54:57]
	v_mfma_f32_16x16x32_bf16 v[46:49], v[178:181], v[202:205], v[46:49]
	v_mfma_f32_16x16x32_bf16 v[38:41], v[162:165], v[210:213], v[38:41]
	v_mfma_f32_16x16x32_bf16 v[34:37], v[178:181], v[210:213], v[34:37]
	s_barrier
	s_add_i32 s59, s59, s44
	v_lshl_add_u64 v[214:215], s[26:27], 0, v[132:133]
	s_mov_b32 m0, s59
	ds_read_b128 v[182:185], v173 offset:16384
	ds_read_b128 v[186:189], v173 offset:17408
	ds_read_b128 v[190:193], v173 offset:18432
	ds_read_b128 v[194:197], v173 offset:19456
	ds_read_b128 v[198:201], v173 offset:20480
	ds_read_b128 v[202:205], v173 offset:21504
	ds_read_b128 v[206:209], v173 offset:22528
	ds_read_b128 v[210:213], v173 offset:23552
	global_load_lds_dwordx4 v[214:215], off
	s_add_i32 m0, s59, 0x2000
	s_add_u32 s60, s26, 0x40000
	v_lshl_add_u64 v[216:217], s[26:27], 0, v[136:137]
	s_addc_u32 s61, s27, 0
	s_add_i32 s59, s62, s44
	global_load_lds_dwordx4 v[216:217], off
	v_lshl_add_u64 v[218:219], s[60:61], 0, v[132:133]
	s_mov_b32 m0, s59
	v_lshl_add_u64 v[220:221], vcc, 0, v[134:135]
	global_load_lds_dwordx4 v[218:219], off
	v_lshl_add_u64 v[218:219], s[60:61], 0, v[136:137]
	s_add_i32 m0, s59, 0x2000
	s_nop 0
	global_load_lds_dwordx4 v[218:219], off
	v_lshl_add_u64 v[218:219], vcc, 0, v[130:131]
	s_mov_b32 m0, s23
	s_nop 0
	global_load_lds_dwordx4 v[218:219], off
	s_mov_b32 m0, s45
	s_nop 0
	global_load_lds_dwordx4 v[220:221], off
	s_waitcnt vmcnt(8)
	s_waitcnt lgkmcnt(0)
	s_barrier
	s_waitcnt lgkmcnt(0)
	v_mfma_f32_16x16x32_bf16 v[94:97], v[142:145], v[182:185], 0
	v_mfma_f32_16x16x32_bf16 v[90:93], v[150:153], v[182:185], 0
	v_mfma_f32_16x16x32_bf16 v[86:89], v[142:145], v[190:193], 0
	v_mfma_f32_16x16x32_bf16 v[78:81], v[150:153], v[190:193], 0
	v_mfma_f32_16x16x32_bf16 v[66:69], v[142:145], v[198:201], 0
	v_mfma_f32_16x16x32_bf16 v[58:61], v[150:153], v[198:201], 0
	v_mfma_f32_16x16x32_bf16 v[50:53], v[142:145], v[206:209], 0
	v_mfma_f32_16x16x32_bf16 v[42:45], v[150:153], v[206:209], 0
	v_mfma_f32_16x16x32_bf16 v[94:97], v[146:149], v[186:189], v[94:97]
	v_mfma_f32_16x16x32_bf16 v[90:93], v[154:157], v[186:189], v[90:93]
	v_mfma_f32_16x16x32_bf16 v[86:89], v[146:149], v[194:197], v[86:89]
	v_mfma_f32_16x16x32_bf16 v[78:81], v[154:157], v[194:197], v[78:81]
	v_mfma_f32_16x16x32_bf16 v[66:69], v[146:149], v[202:205], v[66:69]
	v_mfma_f32_16x16x32_bf16 v[58:61], v[154:157], v[202:205], v[58:61]
	v_mfma_f32_16x16x32_bf16 v[50:53], v[146:149], v[210:213], v[50:53]
	v_mfma_f32_16x16x32_bf16 v[42:45], v[154:157], v[210:213], v[42:45]
	v_mfma_f32_16x16x32_bf16 v[30:33], v[158:161], v[182:185], 0
	v_mfma_f32_16x16x32_bf16 v[26:29], v[174:177], v[182:185], 0
	v_mfma_f32_16x16x32_bf16 v[22:25], v[158:161], v[190:193], 0
	v_mfma_f32_16x16x32_bf16 v[18:21], v[174:177], v[190:193], 0
	v_mfma_f32_16x16x32_bf16 v[14:17], v[158:161], v[198:201], 0
	v_mfma_f32_16x16x32_bf16 v[10:13], v[174:177], v[198:201], 0
	v_mfma_f32_16x16x32_bf16 v[6:9], v[158:161], v[206:209], 0
	v_mfma_f32_16x16x32_bf16 v[2:5], v[174:177], v[206:209], 0
	v_mfma_f32_16x16x32_bf16 v[30:33], v[162:165], v[186:189], v[30:33]
	v_mfma_f32_16x16x32_bf16 v[26:29], v[178:181], v[186:189], v[26:29]
	v_mfma_f32_16x16x32_bf16 v[22:25], v[162:165], v[194:197], v[22:25]
	v_mfma_f32_16x16x32_bf16 v[18:21], v[178:181], v[194:197], v[18:21]
	v_mfma_f32_16x16x32_bf16 v[14:17], v[162:165], v[202:205], v[14:17]
	v_mfma_f32_16x16x32_bf16 v[10:13], v[178:181], v[202:205], v[10:13]
	v_mfma_f32_16x16x32_bf16 v[6:9], v[162:165], v[210:213], v[6:9]
	v_mfma_f32_16x16x32_bf16 v[2:5], v[178:181], v[210:213], v[2:5]
	s_barrier
	s_add_i32 s59, 0, 0x18000
	v_add_u32_e32 v0, s59, v167
	s_add_i32 s62, 0, 0x1c000
	ds_read_b128 v[142:145], v0
	ds_read_b128 v[146:149], v0 offset:1024
	ds_read_b128 v[150:153], v0 offset:2048
	ds_read_b128 v[154:157], v0 offset:3072
	v_add_u32_e32 v0, s62, v167
	ds_read_b128 v[158:161], v0
	ds_read_b128 v[162:165], v0 offset:1024
	ds_read_b128 v[174:177], v0 offset:2048
	ds_read_b128 v[178:181], v0 offset:3072
	s_add_u32 s60, vcc_lo, 0x40000
	s_addc_u32 s61, vcc_hi, 0
	s_mov_b32 m0, s47
	v_lshl_add_u64 v[222:223], s[60:61], 0, v[130:131]
	ds_read_b128 v[182:185], v173 offset:32768
	ds_read_b128 v[186:189], v173 offset:33792
	ds_read_b128 v[190:193], v173 offset:34816
	ds_read_b128 v[194:197], v173 offset:35840
	ds_read_b128 v[198:201], v173 offset:36864
	ds_read_b128 v[202:205], v173 offset:37888
	ds_read_b128 v[206:209], v173 offset:38912
	ds_read_b128 v[210:213], v173 offset:39936
	global_load_lds_dwordx4 v[222:223], off
	v_lshl_add_u64 v[222:223], s[60:61], 0, v[134:135]
	s_mov_b32 m0, s49
	s_nop 0
	global_load_lds_dwordx4 v[222:223], off
	s_waitcnt vmcnt(8)
	s_waitcnt lgkmcnt(0)
	s_barrier
	s_waitcnt lgkmcnt(0)
	v_mfma_f32_16x16x32_bf16 v[126:129], v[142:145], v[182:185], v[126:129]
	v_mfma_f32_16x16x32_bf16 v[122:125], v[150:153], v[182:185], v[122:125]
	v_mfma_f32_16x16x32_bf16 v[118:121], v[142:145], v[190:193], v[118:121]
	v_mfma_f32_16x16x32_bf16 v[114:117], v[150:153], v[190:193], v[114:117]
	v_mfma_f32_16x16x32_bf16 v[110:113], v[142:145], v[198:201], v[110:113]
	v_mfma_f32_16x16x32_bf16 v[106:109], v[150:153], v[198:201], v[106:109]
	v_mfma_f32_16x16x32_bf16 v[102:105], v[142:145], v[206:209], v[102:105]
	v_mfma_f32_16x16x32_bf16 v[98:101], v[150:153], v[206:209], v[98:101]
	v_mfma_f32_16x16x32_bf16 v[126:129], v[146:149], v[186:189], v[126:129]
	v_mfma_f32_16x16x32_bf16 v[122:125], v[154:157], v[186:189], v[122:125]
	v_mfma_f32_16x16x32_bf16 v[118:121], v[146:149], v[194:197], v[118:121]
	v_mfma_f32_16x16x32_bf16 v[114:117], v[154:157], v[194:197], v[114:117]
	v_mfma_f32_16x16x32_bf16 v[110:113], v[146:149], v[202:205], v[110:113]
	v_mfma_f32_16x16x32_bf16 v[106:109], v[154:157], v[202:205], v[106:109]
	v_mfma_f32_16x16x32_bf16 v[102:105], v[146:149], v[210:213], v[102:105]
	v_mfma_f32_16x16x32_bf16 v[98:101], v[154:157], v[210:213], v[98:101]
	v_mfma_f32_16x16x32_bf16 v[82:85], v[158:161], v[182:185], v[82:85]
	v_mfma_f32_16x16x32_bf16 v[74:77], v[174:177], v[182:185], v[74:77]
	v_mfma_f32_16x16x32_bf16 v[70:73], v[158:161], v[190:193], v[70:73]
	v_mfma_f32_16x16x32_bf16 v[62:65], v[174:177], v[190:193], v[62:65]
	v_mfma_f32_16x16x32_bf16 v[54:57], v[158:161], v[198:201], v[54:57]
	v_mfma_f32_16x16x32_bf16 v[46:49], v[174:177], v[198:201], v[46:49]
	v_mfma_f32_16x16x32_bf16 v[38:41], v[158:161], v[206:209], v[38:41]
	v_mfma_f32_16x16x32_bf16 v[34:37], v[174:177], v[206:209], v[34:37]
	v_mfma_f32_16x16x32_bf16 v[82:85], v[162:165], v[186:189], v[82:85]
	v_mfma_f32_16x16x32_bf16 v[74:77], v[178:181], v[186:189], v[74:77]
	v_mfma_f32_16x16x32_bf16 v[70:73], v[162:165], v[194:197], v[70:73]
	v_mfma_f32_16x16x32_bf16 v[62:65], v[178:181], v[194:197], v[62:65]
	v_mfma_f32_16x16x32_bf16 v[54:57], v[162:165], v[202:205], v[54:57]
	v_mfma_f32_16x16x32_bf16 v[46:49], v[178:181], v[202:205], v[46:49]
	v_mfma_f32_16x16x32_bf16 v[38:41], v[162:165], v[210:213], v[38:41]
	v_mfma_f32_16x16x32_bf16 v[34:37], v[178:181], v[210:213], v[34:37]
	s_barrier
	s_add_i32 s59, s59, s44
	v_lshl_add_u64 v[214:215], v[214:215], 0, s[98:99]
	s_mov_b32 m0, s59
	ds_read_b128 v[182:185], v173 offset:49152
	ds_read_b128 v[186:189], v173 offset:50176
	ds_read_b128 v[190:193], v173 offset:51200
	ds_read_b128 v[194:197], v173 offset:52224
	ds_read_b128 v[198:201], v173 offset:53248
	ds_read_b128 v[202:205], v173 offset:54272
	ds_read_b128 v[206:209], v173 offset:55296
	ds_read_b128 v[210:213], v173 offset:56320
	global_load_lds_dwordx4 v[214:215], off
	s_add_i32 m0, s59, 0x2000
	s_add_u32 s26, s26, 0x40080
	v_lshl_add_u64 v[214:215], v[216:217], 0, s[98:99]
	s_addc_u32 s27, s27, 0
	s_add_i32 s59, s62, s44
	global_load_lds_dwordx4 v[214:215], off
	v_lshl_add_u64 v[214:215], s[26:27], 0, v[132:133]
	s_mov_b32 m0, s59
	s_nop 0
	global_load_lds_dwordx4 v[214:215], off
	v_lshl_add_u64 v[214:215], s[26:27], 0, v[136:137]
	s_add_i32 m0, s59, 0x2000
	s_nop 0
	global_load_lds_dwordx4 v[214:215], off
	v_lshl_add_u64 v[214:215], v[218:219], 0, s[98:99]
	s_mov_b32 m0, s52
	s_nop 0
	global_load_lds_dwordx4 v[214:215], off
	v_lshl_add_u64 v[214:215], v[220:221], 0, s[98:99]
	s_mov_b32 m0, s53
	s_nop 0
	global_load_lds_dwordx4 v[214:215], off
	s_waitcnt vmcnt(8)
	s_waitcnt lgkmcnt(0)
	s_barrier
	s_waitcnt lgkmcnt(0)
	v_mfma_f32_16x16x32_bf16 v[94:97], v[142:145], v[182:185], v[94:97]
	v_mfma_f32_16x16x32_bf16 v[90:93], v[150:153], v[182:185], v[90:93]
	v_mfma_f32_16x16x32_bf16 v[86:89], v[142:145], v[190:193], v[86:89]
	v_mfma_f32_16x16x32_bf16 v[78:81], v[150:153], v[190:193], v[78:81]
	v_mfma_f32_16x16x32_bf16 v[66:69], v[142:145], v[198:201], v[66:69]
	v_mfma_f32_16x16x32_bf16 v[58:61], v[150:153], v[198:201], v[58:61]
	v_mfma_f32_16x16x32_bf16 v[50:53], v[142:145], v[206:209], v[50:53]
	v_mfma_f32_16x16x32_bf16 v[42:45], v[150:153], v[206:209], v[42:45]
	v_mfma_f32_16x16x32_bf16 v[94:97], v[146:149], v[186:189], v[94:97]
	v_mfma_f32_16x16x32_bf16 v[90:93], v[154:157], v[186:189], v[90:93]
	v_mfma_f32_16x16x32_bf16 v[86:89], v[146:149], v[194:197], v[86:89]
	v_mfma_f32_16x16x32_bf16 v[78:81], v[154:157], v[194:197], v[78:81]
	v_mfma_f32_16x16x32_bf16 v[66:69], v[146:149], v[202:205], v[66:69]
	v_mfma_f32_16x16x32_bf16 v[58:61], v[154:157], v[202:205], v[58:61]
	v_mfma_f32_16x16x32_bf16 v[50:53], v[146:149], v[210:213], v[50:53]
	v_mfma_f32_16x16x32_bf16 v[42:45], v[154:157], v[210:213], v[42:45]
	v_mfma_f32_16x16x32_bf16 v[30:33], v[158:161], v[182:185], v[30:33]
	v_mfma_f32_16x16x32_bf16 v[26:29], v[174:177], v[182:185], v[26:29]
	v_mfma_f32_16x16x32_bf16 v[22:25], v[158:161], v[190:193], v[22:25]
	v_mfma_f32_16x16x32_bf16 v[18:21], v[174:177], v[190:193], v[18:21]
	v_mfma_f32_16x16x32_bf16 v[14:17], v[158:161], v[198:201], v[14:17]
	v_mfma_f32_16x16x32_bf16 v[10:13], v[174:177], v[198:201], v[10:13]
	v_mfma_f32_16x16x32_bf16 v[6:9], v[158:161], v[206:209], v[6:9]
	v_mfma_f32_16x16x32_bf16 v[2:5], v[174:177], v[206:209], v[2:5]
	v_mfma_f32_16x16x32_bf16 v[30:33], v[162:165], v[186:189], v[30:33]
	v_mfma_f32_16x16x32_bf16 v[26:29], v[178:181], v[186:189], v[26:29]
	v_mfma_f32_16x16x32_bf16 v[22:25], v[162:165], v[194:197], v[22:25]
	v_mfma_f32_16x16x32_bf16 v[18:21], v[178:181], v[194:197], v[18:21]
	v_mfma_f32_16x16x32_bf16 v[14:17], v[162:165], v[202:205], v[14:17]
	v_mfma_f32_16x16x32_bf16 v[10:13], v[178:181], v[202:205], v[10:13]
	v_mfma_f32_16x16x32_bf16 v[6:9], v[162:165], v[210:213], v[6:9]
	v_mfma_f32_16x16x32_bf16 v[2:5], v[178:181], v[210:213], v[2:5]
	s_barrier
	s_add_i32 s58, s58, 2
	s_add_u32 s40, s40, 0x100
	s_addc_u32 s41, s41, 0
	s_add_u32 s56, s56, 0x100
	s_addc_u32 s57, s57, 0
	s_cmp_gt_u32 s58, 13
	s_cbranch_scc1 .Lpeel_done_160

.LBB0_163:
	s_cmp_eq_u32 s64, 0
	s_cbranch_scc1 .Lks_norm
	s_nop 7
	s_lshr_b32 s66, s2, 1
	s_lshl_b32 s67, s66, 18
	s_add_u32 s68, s34, 0x5200000
	s_addc_u32 s69, s35, 0
	s_add_u32 s68, s68, s67
	s_addc_u32 s69, s69, 0
	s_lshl_b32 s67, s66, 2
	s_sub_u32 s72, s34, 0x8f90000
	s_subb_u32 s73, s35, 0
	s_add_u32 s72, s72, s67
	s_addc_u32 s73, s73, 0
	s_mov_b32 s70, 0x1000
	s_mov_b32 s71, 0
	v_lshrrev_b32_e32 v244, 6, v224
	v_and_b32_e32 v245, 63, v224
	v_lshlrev_b32_e32 v244, 15, v244
	v_lshl_or_b32 v244, v245, 4, v244
	v_mov_b32_e32 v245, 0
	v_lshl_add_u64 v[244:245], s[68:69], 0, v[244:245]
	s_cmp_eq_u32 s64, 2
	s_cbranch_scc1 .Lks_cons
	global_store_dwordx4 v[244:245], v[2:5], off sc1
	global_store_dwordx4 v[244:245], v[6:9], off offset:1024 sc1
	global_store_dwordx4 v[244:245], v[10:13], off offset:2048 sc1
	global_store_dwordx4 v[244:245], v[14:17], off offset:3072 sc1
	v_lshl_add_u64 v[244:245], v[244:245], 0, s[70:71]
	global_store_dwordx4 v[244:245], v[18:21], off sc1
	global_store_dwordx4 v[244:245], v[22:25], off offset:1024 sc1
	global_store_dwordx4 v[244:245], v[26:29], off offset:2048 sc1
	global_store_dwordx4 v[244:245], v[30:33], off offset:3072 sc1
	v_lshl_add_u64 v[244:245], v[244:245], 0, s[70:71]
	global_store_dwordx4 v[244:245], v[34:37], off sc1
	global_store_dwordx4 v[244:245], v[38:41], off offset:1024 sc1
	global_store_dwordx4 v[244:245], v[42:45], off offset:2048 sc1
	global_store_dwordx4 v[244:245], v[46:49], off offset:3072 sc1
	v_lshl_add_u64 v[244:245], v[244:245], 0, s[70:71]
	global_store_dwordx4 v[244:245], v[50:53], off sc1
	global_store_dwordx4 v[244:245], v[54:57], off offset:1024 sc1
	global_store_dwordx4 v[244:245], v[58:61], off offset:2048 sc1
	global_store_dwordx4 v[244:245], v[62:65], off offset:3072 sc1
	v_lshl_add_u64 v[244:245], v[244:245], 0, s[70:71]
	global_store_dwordx4 v[244:245], v[66:69], off sc1
	global_store_dwordx4 v[244:245], v[70:73], off offset:1024 sc1
	global_store_dwordx4 v[244:245], v[74:77], off offset:2048 sc1
	global_store_dwordx4 v[244:245], v[78:81], off offset:3072 sc1
	v_lshl_add_u64 v[244:245], v[244:245], 0, s[70:71]
	global_store_dwordx4 v[244:245], v[82:85], off sc1
	global_store_dwordx4 v[244:245], v[86:89], off offset:1024 sc1
	global_store_dwordx4 v[244:245], v[90:93], off offset:2048 sc1
	global_store_dwordx4 v[244:245], v[94:97], off offset:3072 sc1
	v_lshl_add_u64 v[244:245], v[244:245], 0, s[70:71]
	global_store_dwordx4 v[244:245], v[98:101], off sc1
	global_store_dwordx4 v[244:245], v[102:105], off offset:1024 sc1
	global_store_dwordx4 v[244:245], v[106:109], off offset:2048 sc1
	global_store_dwordx4 v[244:245], v[110:113], off offset:3072 sc1
	v_lshl_add_u64 v[244:245], v[244:245], 0, s[70:71]
	global_store_dwordx4 v[244:245], v[114:117], off sc1
	global_store_dwordx4 v[244:245], v[118:121], off offset:1024 sc1
	global_store_dwordx4 v[244:245], v[122:125], off offset:2048 sc1
	global_store_dwordx4 v[244:245], v[126:129], off offset:3072 sc1
	s_waitcnt vmcnt(0)
	v_mov_b32_e32 v246, 1
	s_mov_b64 exec, 1
	global_atomic_add v1, v246, s[72:73]
	s_mov_b64 exec, -1
	s_waitcnt vmcnt(0)
	s_branch .LBB0_181
.Lks_cons:
	s_cmp_gt_u32 s3, 9
	s_cselect_b32 s67, 16, 8
	s_mov_b32 s75, 0
.Lks_spin:
	global_load_dword v246, v1, s[72:73] sc1
	s_waitcnt vmcnt(0)
	v_readfirstlane_b32 s74, v246
	s_cmp_ge_u32 s74, s67
	s_cbranch_scc1 .Lks_go
	s_sleep 2
	s_add_i32 s75, s75, 1
	s_cmp_lt_u32 s75, 0x4000
	s_cbranch_scc1 .Lks_spin
.Lks_go:
	global_load_dwordx4 v[142:145], v[244:245], off sc1
	global_load_dwordx4 v[146:149], v[244:245], off offset:1024 sc1
	global_load_dwordx4 v[150:153], v[244:245], off offset:2048 sc1
	global_load_dwordx4 v[154:157], v[244:245], off offset:3072 sc1
	v_lshl_add_u64 v[244:245], v[244:245], 0, s[70:71]
	global_load_dwordx4 v[158:161], v[244:245], off sc1
	global_load_dwordx4 v[162:165], v[244:245], off offset:1024 sc1
	global_load_dwordx4 v[174:177], v[244:245], off offset:2048 sc1
	global_load_dwordx4 v[178:181], v[244:245], off offset:3072 sc1
	v_lshl_add_u64 v[244:245], v[244:245], 0, s[70:71]
	global_load_dwordx4 v[182:185], v[244:245], off sc1
	global_load_dwordx4 v[186:189], v[244:245], off offset:1024 sc1
	global_load_dwordx4 v[190:193], v[244:245], off offset:2048 sc1
	global_load_dwordx4 v[194:197], v[244:245], off offset:3072 sc1
	v_lshl_add_u64 v[244:245], v[244:245], 0, s[70:71]
	global_load_dwordx4 v[198:201], v[244:245], off sc1
	global_load_dwordx4 v[202:205], v[244:245], off offset:1024 sc1
	global_load_dwordx4 v[206:209], v[244:245], off offset:2048 sc1
	global_load_dwordx4 v[210:213], v[244:245], off offset:3072 sc1
	v_lshl_add_u64 v[244:245], v[244:245], 0, s[70:71]
	s_waitcnt vmcnt(15)
	v_pk_add_f32 v[2:3], v[2:3], v[142:143]
	v_pk_add_f32 v[4:5], v[4:5], v[144:145]
	s_waitcnt vmcnt(14)
	v_pk_add_f32 v[6:7], v[6:7], v[146:147]
	v_pk_add_f32 v[8:9], v[8:9], v[148:149]
	s_waitcnt vmcnt(13)
	v_pk_add_f32 v[10:11], v[10:11], v[150:151]
	v_pk_add_f32 v[12:13], v[12:13], v[152:153]
	s_waitcnt vmcnt(12)
	v_pk_add_f32 v[14:15], v[14:15], v[154:155]
	v_pk_add_f32 v[16:17], v[16:17], v[156:157]
	s_waitcnt vmcnt(11)
	v_pk_add_f32 v[18:19], v[18:19], v[158:159]
	v_pk_add_f32 v[20:21], v[20:21], v[160:161]
	s_waitcnt vmcnt(10)
	v_pk_add_f32 v[22:23], v[22:23], v[162:163]
	v_pk_add_f32 v[24:25], v[24:25], v[164:165]
	s_waitcnt vmcnt(9)
	v_pk_add_f32 v[26:27], v[26:27], v[174:175]
	v_pk_add_f32 v[28:29], v[28:29], v[176:177]
	s_waitcnt vmcnt(8)
	v_pk_add_f32 v[30:31], v[30:31], v[178:179]
	v_pk_add_f32 v[32:33], v[32:33], v[180:181]
	s_waitcnt vmcnt(7)
	v_pk_add_f32 v[34:35], v[34:35], v[182:183]
	v_pk_add_f32 v[36:37], v[36:37], v[184:185]
	s_waitcnt vmcnt(6)
	v_pk_add_f32 v[38:39], v[38:39], v[186:187]
	v_pk_add_f32 v[40:41], v[40:41], v[188:189]
	s_waitcnt vmcnt(5)
	v_pk_add_f32 v[42:43], v[42:43], v[190:191]
	v_pk_add_f32 v[44:45], v[44:45], v[192:193]
	s_waitcnt vmcnt(4)
	v_pk_add_f32 v[46:47], v[46:47], v[194:195]
	v_pk_add_f32 v[48:49], v[48:49], v[196:197]
	s_waitcnt vmcnt(3)
	v_pk_add_f32 v[50:51], v[50:51], v[198:199]
	v_pk_add_f32 v[52:53], v[52:53], v[200:201]
	s_waitcnt vmcnt(2)
	v_pk_add_f32 v[54:55], v[54:55], v[202:203]
	v_pk_add_f32 v[56:57], v[56:57], v[204:205]
	s_waitcnt vmcnt(1)
	v_pk_add_f32 v[58:59], v[58:59], v[206:207]
	v_pk_add_f32 v[60:61], v[60:61], v[208:209]
	s_waitcnt vmcnt(0)
	v_pk_add_f32 v[62:63], v[62:63], v[210:211]
	v_pk_add_f32 v[64:65], v[64:65], v[212:213]
	global_load_dwordx4 v[142:145], v[244:245], off sc1
	global_load_dwordx4 v[146:149], v[244:245], off offset:1024 sc1
	global_load_dwordx4 v[150:153], v[244:245], off offset:2048 sc1
	global_load_dwordx4 v[154:157], v[244:245], off offset:3072 sc1
	v_lshl_add_u64 v[244:245], v[244:245], 0, s[70:71]
	global_load_dwordx4 v[158:161], v[244:245], off sc1
	global_load_dwordx4 v[162:165], v[244:245], off offset:1024 sc1
	global_load_dwordx4 v[174:177], v[244:245], off offset:2048 sc1
	global_load_dwordx4 v[178:181], v[244:245], off offset:3072 sc1
	v_lshl_add_u64 v[244:245], v[244:245], 0, s[70:71]
	global_load_dwordx4 v[182:185], v[244:245], off sc1
	global_load_dwordx4 v[186:189], v[244:245], off offset:1024 sc1
	global_load_dwordx4 v[190:193], v[244:245], off offset:2048 sc1
	global_load_dwordx4 v[194:197], v[244:245], off offset:3072 sc1
	v_lshl_add_u64 v[244:245], v[244:245], 0, s[70:71]
	global_load_dwordx4 v[198:201], v[244:245], off sc1
	global_load_dwordx4 v[202:205], v[244:245], off offset:1024 sc1
	global_load_dwordx4 v[206:209], v[244:245], off offset:2048 sc1
	global_load_dwordx4 v[210:213], v[244:245], off offset:3072 sc1
	s_waitcnt vmcnt(15)
	v_pk_add_f32 v[66:67], v[66:67], v[142:143]
	v_pk_add_f32 v[68:69], v[68:69], v[144:145]
	s_waitcnt vmcnt(14)
	v_pk_add_f32 v[70:71], v[70:71], v[146:147]
	v_pk_add_f32 v[72:73], v[72:73], v[148:149]
	s_waitcnt vmcnt(13)
	v_pk_add_f32 v[74:75], v[74:75], v[150:151]
	v_pk_add_f32 v[76:77], v[76:77], v[152:153]
	s_waitcnt vmcnt(12)
	v_pk_add_f32 v[78:79], v[78:79], v[154:155]
	v_pk_add_f32 v[80:81], v[80:81], v[156:157]
	s_waitcnt vmcnt(11)
	v_pk_add_f32 v[82:83], v[82:83], v[158:159]
	v_pk_add_f32 v[84:85], v[84:85], v[160:161]
	s_waitcnt vmcnt(10)
	v_pk_add_f32 v[86:87], v[86:87], v[162:163]
	v_pk_add_f32 v[88:89], v[88:89], v[164:165]
	s_waitcnt vmcnt(9)
	v_pk_add_f32 v[90:91], v[90:91], v[174:175]
	v_pk_add_f32 v[92:93], v[92:93], v[176:177]
	s_waitcnt vmcnt(8)
	v_pk_add_f32 v[94:95], v[94:95], v[178:179]
	v_pk_add_f32 v[96:97], v[96:97], v[180:181]
	s_waitcnt vmcnt(7)
	v_pk_add_f32 v[98:99], v[98:99], v[182:183]
	v_pk_add_f32 v[100:101], v[100:101], v[184:185]
	s_waitcnt vmcnt(6)
	v_pk_add_f32 v[102:103], v[102:103], v[186:187]
	v_pk_add_f32 v[104:105], v[104:105], v[188:189]
	s_waitcnt vmcnt(5)
	v_pk_add_f32 v[106:107], v[106:107], v[190:191]
	v_pk_add_f32 v[108:109], v[108:109], v[192:193]
	s_waitcnt vmcnt(4)
	v_pk_add_f32 v[110:111], v[110:111], v[194:195]
	v_pk_add_f32 v[112:113], v[112:113], v[196:197]
	s_waitcnt vmcnt(3)
	v_pk_add_f32 v[114:115], v[114:115], v[198:199]
	v_pk_add_f32 v[116:117], v[116:117], v[200:201]
	s_waitcnt vmcnt(2)
	v_pk_add_f32 v[118:119], v[118:119], v[202:203]
	v_pk_add_f32 v[120:121], v[120:121], v[204:205]
	s_waitcnt vmcnt(1)
	v_pk_add_f32 v[122:123], v[122:123], v[206:207]
	v_pk_add_f32 v[124:125], v[124:125], v[208:209]
	s_waitcnt vmcnt(0)
	v_pk_add_f32 v[126:127], v[126:127], v[210:211]
	v_pk_add_f32 v[128:129], v[128:129], v[212:213]

	.amdhsa_kernel _Z14fwd_megakernel4Args
		.amdhsa_group_segment_fixed_size 0
		.amdhsa_private_segment_fixed_size 0
		.amdhsa_kernarg_size 424
		.amdhsa_user_sgpr_count 2
		.amdhsa_user_sgpr_dispatch_ptr 0
		.amdhsa_user_sgpr_queue_ptr 0
		.amdhsa_user_sgpr_kernarg_segment_ptr 1
		.amdhsa_user_sgpr_dispatch_id 0
		.amdhsa_user_sgpr_kernarg_preload_length 0
		.amdhsa_user_sgpr_kernarg_preload_offset 0
		.amdhsa_user_sgpr_private_segment_size 0
		.amdhsa_uses_dynamic_stack 0
		.amdhsa_enable_private_segment 0
		.amdhsa_system_sgpr_workgroup_id_x 1
		.amdhsa_system_sgpr_workgroup_id_y 0
		.amdhsa_system_sgpr_workgroup_id_z 0
		.amdhsa_system_sgpr_workgroup_info 0
		.amdhsa_system_vgpr_workitem_id 2
		.amdhsa_next_free_vgpr 256
		.amdhsa_next_free_sgpr 100
		.amdhsa_accum_offset 256
		.amdhsa_reserve_vcc 1
		.amdhsa_float_round_mode_32 0
		.amdhsa_float_round_mode_16_64 0
		.amdhsa_float_denorm_mode_32 3
		.amdhsa_float_denorm_mode_16_64 3
		.amdhsa_dx10_clamp 1
		.amdhsa_ieee_mode 1
		.amdhsa_fp16_overflow 0
		.amdhsa_tg_split 0
		.amdhsa_exception_fp_ieee_invalid_op 0
		.amdhsa_exception_fp_denorm_src 0
		.amdhsa_exception_fp_ieee_div_zero 0
		.amdhsa_exception_fp_ieee_overflow 0
		.amdhsa_exception_fp_ieee_underflow 0
		.amdhsa_exception_fp_ieee_inexact 0
		.amdhsa_exception_int_div_zero 0
	.end_amdhsa_kernel

.Lfunc_end0:
	.size	_Z14fwd_megakernel4Args, .Lfunc_end0-_Z14fwd_megakernel4Args
	.set _Z14fwd_megakernel4Args.num_vgpr, 256
	.set _Z14fwd_megakernel4Args.num_agpr, 0
	.set _Z14fwd_megakernel4Args.numbered_sgpr, 100
	.set _Z14fwd_megakernel4Args.num_named_barrier, 0
	.set _Z14fwd_megakernel4Args.private_seg_size, 0
	.set _Z14fwd_megakernel4Args.uses_vcc, 1
	.set _Z14fwd_megakernel4Args.uses_flat_scratch, 0
	.set _Z14fwd_megakernel4Args.has_dyn_sized_stack, 0
	.set _Z14fwd_megakernel4Args.has_recursion, 0
	.set _Z14fwd_megakernel4Args.has_indirect_call, 0

amdhsa.kernels:
  - .agpr_count:     0
    .args:
      - .offset:         0
        .size:           168
        .value_kind:     by_value
      - .offset:         168
        .size:           4
        .value_kind:     hidden_block_count_x
      - .offset:         172
        .size:           4
        .value_kind:     hidden_block_count_y
      - .offset:         176
        .size:           4
        .value_kind:     hidden_block_count_z
      - .offset:         180
        .size:           2
        .value_kind:     hidden_group_size_x
      - .offset:         182
        .size:           2
        .value_kind:     hidden_group_size_y
      - .offset:         184
        .size:           2
        .value_kind:     hidden_group_size_z
      - .offset:         186
        .size:           2
        .value_kind:     hidden_remainder_x
      - .offset:         188
        .size:           2
        .value_kind:     hidden_remainder_y
      - .offset:         190
        .size:           2
        .value_kind:     hidden_remainder_z
      - .offset:         208
        .size:           8
        .value_kind:     hidden_global_offset_x
      - .offset:         216
        .size:           8
        .value_kind:     hidden_global_offset_y
      - .offset:         224
        .size:           8
        .value_kind:     hidden_global_offset_z
      - .offset:         232
        .size:           2
        .value_kind:     hidden_grid_dims
      - .offset:         256
        .size:           8
        .value_kind:     hidden_multigrid_sync_arg
      - .offset:         288
        .size:           4
        .value_kind:     hidden_dynamic_lds_size
    .group_segment_fixed_size: 0
    .kernarg_segment_align: 8
    .kernarg_segment_size: 424
    .language:       OpenCL C
    .language_version:
      - 2
      - 0
    .max_flat_workgroup_size: 512
    .name:           _Z14fwd_megakernel4Args
    .private_segment_fixed_size: 0
    .sgpr_count:     106
    .sgpr_spill_count: 76
    .symbol:         _Z14fwd_megakernel4Args.kd
    .uniform_work_group_size: 1
    .uses_dynamic_stack: false
    .vgpr_count:     256
    .vgpr_spill_count: 0
    .wavefront_size: 64
